# v12 + PV MFMAs rebalanced across the softmax VALU stream + static s_setprio 1 for waves 4-7 around the diff tile loop
# speedup vs baseline: 1.0145x; 1.0014x over previous
.LBB0_757:
	v_mov_b32_e32 v14, v0
	v_mov_b32_e32 v15, v0
	v_mov_b32_e32 v1, v0
	v_mov_b32_e32 v2, v0
	v_mov_b32_e32 v3, v0
	v_mov_b32_e32 v4, v0
	v_mov_b32_e32 v5, v0
	v_mov_b32_e32 v6, v0
	v_mov_b32_e32 v7, v0
	v_mov_b32_e32 v8, v0
	v_mov_b32_e32 v9, v0
	v_mov_b32_e32 v10, v0
	v_mov_b32_e32 v11, v0
	v_mov_b32_e32 v12, v0
	v_mov_b32_e32 v13, v0
	v_mov_b64_e32 v[30:31], v[14:15]
	v_mov_b64_e32 v[46:47], v[14:15]
	v_mov_b64_e32 v[62:63], v[14:15]
	v_mov_b64_e32 v[78:79], v[14:15]
	s_xor_b64 s[0:1], s[0:1], -1
	v_lshl_add_u64 v[188:189], s[14:15], 1, v[180:181]
	s_mov_b32 s25, 0
	v_mov_b32_e32 v187, 0
	v_mov_b32_e32 v208, 0xff800000
	s_mov_b64 s[4:5], 0
	s_mov_b32 s26, s21
	v_mov_b64_e32 v[28:29], v[12:13]
	v_mov_b64_e32 v[26:27], v[10:11]
	v_mov_b64_e32 v[24:25], v[8:9]
	v_mov_b64_e32 v[22:23], v[6:7]
	v_mov_b64_e32 v[20:21], v[4:5]
	v_mov_b64_e32 v[18:19], v[2:3]
	v_mov_b64_e32 v[16:17], v[0:1]
	v_mov_b64_e32 v[44:45], v[12:13]
	v_mov_b64_e32 v[42:43], v[10:11]
	v_mov_b64_e32 v[40:41], v[8:9]
	v_mov_b64_e32 v[38:39], v[6:7]
	v_mov_b64_e32 v[36:37], v[4:5]
	v_mov_b64_e32 v[34:35], v[2:3]
	v_mov_b64_e32 v[32:33], v[0:1]
	v_mov_b64_e32 v[60:61], v[12:13]
	v_mov_b64_e32 v[58:59], v[10:11]
	v_mov_b64_e32 v[56:57], v[8:9]
	v_mov_b64_e32 v[54:55], v[6:7]
	v_mov_b64_e32 v[52:53], v[4:5]
	v_mov_b64_e32 v[50:51], v[2:3]
	v_mov_b64_e32 v[48:49], v[0:1]
	v_mov_b64_e32 v[76:77], v[12:13]
	v_mov_b64_e32 v[74:75], v[10:11]
	v_mov_b64_e32 v[72:73], v[8:9]
	v_mov_b64_e32 v[70:71], v[6:7]
	v_mov_b64_e32 v[68:69], v[4:5]
	v_mov_b64_e32 v[66:67], v[2:3]
	v_mov_b64_e32 v[64:65], v[0:1]
	s_mov_b32 s27, 0
	s_mov_b32 s100, 0
	s_cmp_lt_i32 s3, 4
	s_cbranch_scc1 .Ldq_prio_1
	s_setprio 1
.Ldq_prio_1:
	v_add_u32_e32 v14, v204, v197
	v_add_u32_e32 v15, v204, v198
	ds_read_b128 v[2:5], v14
	ds_read_b128 v[6:9], v14 offset:4096
	ds_read_b128 v[10:13], v209
	ds_read_b128 v[242:245], v15
	ds_read_b128 v[246:249], v15 offset:4096
	ds_read_b128 v[210:213], v209 offset:1024
	s_waitcnt lgkmcnt(3)
	v_mfma_f32_32x32x16_bf16 v[128:143], v[2:5], v[10:13], 0
	v_mfma_f32_32x32x16_bf16 v[112:127], v[6:9], v[10:13], 0
	s_waitcnt lgkmcnt(0)
	v_mfma_f32_32x32x16_bf16 v[128:143], v[242:245], v[210:213], v[128:143]
	v_mfma_f32_32x32x16_bf16 v[112:127], v[246:249], v[210:213], v[112:127]
	v_add_u32_e32 v14, v204, v199
	v_add_u32_e32 v15, v204, v200
	ds_read_b128 v[2:5], v14
	ds_read_b128 v[6:9], v14 offset:4096
	ds_read_b128 v[10:13], v209 offset:2048
	ds_read_b128 v[242:245], v15
	ds_read_b128 v[246:249], v15 offset:4096
	ds_read_b128 v[210:213], v209 offset:3072
	s_waitcnt lgkmcnt(3)
	v_mfma_f32_32x32x16_bf16 v[128:143], v[2:5], v[10:13], v[128:143]
	v_mfma_f32_32x32x16_bf16 v[112:127], v[6:9], v[10:13], v[112:127]
	s_waitcnt lgkmcnt(0)
	v_mfma_f32_32x32x16_bf16 v[128:143], v[242:245], v[210:213], v[128:143]
	v_mfma_f32_32x32x16_bf16 v[112:127], v[246:249], v[210:213], v[112:127]
	s_add_i32 s14, s26, 0xffffff60
	s_cmp_gt_u32 s14, 0xfffffea0
	s_cbranch_scc1 .Ldq_near_2
	s_sub_i32 s14, s26, 31
	s_cmpk_gt_i32 s14, 0x80
	s_cselect_b32 s14, 0x408, 0
	s_add_i32 s14, s18, s14
	v_mov_b32_e32 v1, s14
	ds_read_b32 v14, v1 offset:29312
	s_nop 7
	s_waitcnt lgkmcnt(0)
	s_nop 3
	v_max3_f32 v225, v128, v129, v130
	v_max3_f32 v225, v225, v131, v132
	v_max3_f32 v225, v225, v133, v134
	v_max3_f32 v225, v225, v135, v136
	v_max3_f32 v225, v225, v137, v138
	v_max3_f32 v225, v225, v139, v140
	v_max3_f32 v225, v225, v141, v142
	v_max3_f32 v225, v225, v143, v112
	v_max3_f32 v225, v225, v113, v114
	v_max3_f32 v225, v225, v115, v116
	v_max3_f32 v225, v225, v117, v118
	v_max3_f32 v225, v225, v119, v120
	v_max3_f32 v225, v225, v121, v122
	v_max3_f32 v225, v225, v123, v124
	v_max3_f32 v225, v225, v125, v126
	v_max_f32_e32 v225, v225, v127
	v_fma_f32 v225, v225, s2, v14
	v_mov_b32_e32 v2, v225
	v_mov_b32_e32 v3, v225
	s_nop 1
	v_permlane32_swap_b32 v2, v3
	s_nop 1
	s_nop 0
	v_max3_f32 v225, v225, v2, v3
	v_add_f32_e32 v2, 0x41000000, v208
	v_cmp_gt_f32_e32 vcc, v225, v2
	s_cbranch_vccz .Ldq_norescale_4
	v_max_f32_e32 v2, v225, v225
	v_max_f32_e32 v3, v208, v208
	v_max_f32_e32 v2, v3, v2
	v_sub_f32_e32 v3, v208, v2
	v_exp_f32_e32 v3, v3
	v_mov_b32_e32 v208, v2
	s_nop 0
	v_mul_f32_e32 v187, v187, v3
	v_mov_b32_e32 v214, v3
	s_mov_b32 s100, 1

.Ldq_skipk_7:
	v_lshl_add_u64 v[14:15], v[184:185], 0, s[4:5]
	global_load_dwordx4 v[148:151], v[14:15], off
	v_lshl_add_u64 v[14:15], v[182:183], 0, s[4:5]
	global_load_dwordx4 v[152:155], v[14:15], off
	s_waitcnt lgkmcnt(6)
	v_mfma_f32_32x32x16_bf16 v[128:143], v[2:5], v[10:13], v[128:143]
	v_mfma_f32_32x32x16_bf16 v[112:127], v[6:9], v[10:13], v[112:127]
	s_waitcnt lgkmcnt(3)
	v_mfma_f32_32x32x16_bf16 v[128:143], v[242:245], v[210:213], v[128:143]
	v_mfma_f32_32x32x16_bf16 v[112:127], v[246:249], v[210:213], v[112:127]
	s_add_i32 s14, s26, 0xffffff60
	s_cmp_gt_u32 s14, 0xfffffea0
	s_cbranch_scc1 .Ldq_near_8
	s_sub_i32 s14, s26, 31
	s_cmpk_gt_i32 s14, 0x80
	s_cselect_b32 s14, 0x408, 0
	s_add_i32 s14, s18, s14
	v_mov_b32_e32 v1, s14
	ds_read_b32 v14, v1 offset:29312
	ds_read_b64_tr_b16 v[226:227], v250 offset:29696
	ds_read_b64_tr_b16 v[230:231], v250 offset:29760
	ds_read_b64_tr_b16 v[234:235], v250 offset:29824
	ds_read_b64_tr_b16 v[238:239], v250 offset:29888
	ds_read_b64_tr_b16 v[228:229], v250 offset:32256
	ds_read_b64_tr_b16 v[232:233], v250 offset:32320
	ds_read_b64_tr_b16 v[236:237], v250 offset:32384
	ds_read_b64_tr_b16 v[240:241], v250 offset:32448
	s_waitcnt lgkmcnt(8)
	s_nop 3
	v_mfma_f32_32x32x16_bf16 v[64:79], v[96:99], v[80:83], v[64:79]
	v_max3_f32 v225, v128, v129, v130
	v_max3_f32 v225, v225, v131, v132
	v_max3_f32 v225, v225, v133, v134
	v_max3_f32 v225, v225, v135, v136
	v_mfma_f32_32x32x16_bf16 v[48:63], v[100:103], v[80:83], v[48:63]
	v_max3_f32 v225, v225, v137, v138
	v_max3_f32 v225, v225, v139, v140
	v_max3_f32 v225, v225, v141, v142
	v_max3_f32 v225, v225, v143, v112
	v_mfma_f32_32x32x16_bf16 v[32:47], v[104:107], v[80:83], v[32:47]
	v_max3_f32 v225, v225, v113, v114
	v_max3_f32 v225, v225, v115, v116
	v_max3_f32 v225, v225, v117, v118
	v_max3_f32 v225, v225, v119, v120
	v_mfma_f32_32x32x16_bf16 v[16:31], v[108:111], v[80:83], v[16:31]
	v_max3_f32 v225, v225, v121, v122
	v_max3_f32 v225, v225, v123, v124
	v_max3_f32 v225, v225, v125, v126
	v_max_f32_e32 v225, v225, v127
	ds_read_b64_tr_b16 v[96:97], v250 offset:34816
	ds_read_b64_tr_b16 v[100:101], v250 offset:34880
	ds_read_b64_tr_b16 v[104:105], v250 offset:34944
	ds_read_b64_tr_b16 v[108:109], v250 offset:35008
	ds_read_b64_tr_b16 v[98:99], v250 offset:37376
	ds_read_b64_tr_b16 v[102:103], v250 offset:37440
	ds_read_b64_tr_b16 v[106:107], v250 offset:37504
	ds_read_b64_tr_b16 v[110:111], v250 offset:37568
	v_fma_f32 v225, v225, s2, v14
	v_mov_b32_e32 v2, v225
	v_mov_b32_e32 v3, v225
	s_nop 1
	v_permlane32_swap_b32 v2, v3
	s_nop 1
	s_nop 0
	v_max3_f32 v225, v225, v2, v3
	v_add_f32_e32 v2, 0x41000000, v208
	v_cmp_gt_f32_e32 vcc, v225, v2
	s_cbranch_vccz .Ldq_norescale_10
	v_max_f32_e32 v2, v225, v225
	v_max_f32_e32 v3, v208, v208
	v_max_f32_e32 v2, v3, v2
	v_sub_f32_e32 v3, v208, v2
	v_exp_f32_e32 v3, v3
	v_mov_b32_e32 v208, v2
	s_nop 0
	v_mul_f32_e32 v187, v187, v3
	v_mov_b32_e32 v214, v3
	s_mov_b32 s100, 1
.Ldq_norescale_10:
	v_sub_f32_e32 v14, v14, v208
	s_waitcnt lgkmcnt(8)
	v_mfma_f32_32x32x16_bf16 v[64:79], v[226:229], v[84:87], v[64:79]
	v_fma_f32 v128, v128, s2, v14
	v_fma_f32 v129, v129, s2, v14
	v_exp_f32_e32 v128, v128
	v_exp_f32_e32 v129, v129
	v_mfma_f32_32x32x16_bf16 v[48:63], v[230:233], v[84:87], v[48:63]
	v_fma_f32 v130, v130, s2, v14
	v_fma_f32 v131, v131, s2, v14
	v_exp_f32_e32 v130, v130
	v_exp_f32_e32 v131, v131
	v_mfma_f32_32x32x16_bf16 v[32:47], v[234:237], v[84:87], v[32:47]
	v_fma_f32 v132, v132, s2, v14
	v_fma_f32 v133, v133, s2, v14
	v_exp_f32_e32 v132, v132
	v_exp_f32_e32 v133, v133
	v_fma_f32 v134, v134, s2, v14
	v_fma_f32 v135, v135, s2, v14
	v_exp_f32_e32 v134, v134
	v_exp_f32_e32 v135, v135
	v_mfma_f32_32x32x16_bf16 v[16:31], v[238:241], v[84:87], v[16:31]
	ds_read_b64_tr_b16 v[226:227], v250 offset:39936
	ds_read_b64_tr_b16 v[230:231], v250 offset:40000
	ds_read_b64_tr_b16 v[234:235], v250 offset:40064
	ds_read_b64_tr_b16 v[238:239], v250 offset:40128
	ds_read_b64_tr_b16 v[228:229], v250 offset:42496
	ds_read_b64_tr_b16 v[232:233], v250 offset:42560
	ds_read_b64_tr_b16 v[236:237], v250 offset:42624
	ds_read_b64_tr_b16 v[240:241], v250 offset:42688
	v_fma_f32 v136, v136, s2, v14
	v_fma_f32 v137, v137, s2, v14
	v_exp_f32_e32 v136, v136
	v_exp_f32_e32 v137, v137
	s_waitcnt lgkmcnt(8)
	v_mfma_f32_32x32x16_bf16 v[64:79], v[96:99], v[88:91], v[64:79]
	v_fma_f32 v138, v138, s2, v14
	v_fma_f32 v139, v139, s2, v14
	v_exp_f32_e32 v138, v138
	v_exp_f32_e32 v139, v139
	v_mfma_f32_32x32x16_bf16 v[48:63], v[100:103], v[88:91], v[48:63]
	v_fma_f32 v140, v140, s2, v14
	v_fma_f32 v141, v141, s2, v14
	v_exp_f32_e32 v140, v140
	v_exp_f32_e32 v141, v141
	v_fma_f32 v142, v142, s2, v14
	v_fma_f32 v143, v143, s2, v14
	v_exp_f32_e32 v142, v142
	v_exp_f32_e32 v143, v143
	v_mfma_f32_32x32x16_bf16 v[32:47], v[104:107], v[88:91], v[32:47]
	v_fma_f32 v112, v112, s2, v14
	v_fma_f32 v113, v113, s2, v14
	v_exp_f32_e32 v112, v112
	v_exp_f32_e32 v113, v113
	v_mfma_f32_32x32x16_bf16 v[16:31], v[108:111], v[88:91], v[16:31]
	v_fma_f32 v114, v114, s2, v14
	v_fma_f32 v115, v115, s2, v14
	v_exp_f32_e32 v114, v114
	v_exp_f32_e32 v115, v115
	s_waitcnt lgkmcnt(0)
	v_mfma_f32_32x32x16_bf16 v[64:79], v[226:229], v[92:95], v[64:79]
	v_fma_f32 v116, v116, s2, v14
	v_fma_f32 v117, v117, s2, v14
	v_exp_f32_e32 v116, v116
	v_exp_f32_e32 v117, v117
	v_fma_f32 v118, v118, s2, v14
	v_fma_f32 v119, v119, s2, v14
	v_exp_f32_e32 v118, v118
	v_exp_f32_e32 v119, v119
	v_mfma_f32_32x32x16_bf16 v[48:63], v[230:233], v[92:95], v[48:63]
	v_fma_f32 v120, v120, s2, v14
	v_fma_f32 v121, v121, s2, v14
	v_exp_f32_e32 v120, v120
	v_exp_f32_e32 v121, v121
	v_mfma_f32_32x32x16_bf16 v[32:47], v[234:237], v[92:95], v[32:47]
	v_fma_f32 v122, v122, s2, v14
	v_fma_f32 v123, v123, s2, v14
	v_exp_f32_e32 v122, v122
	v_exp_f32_e32 v123, v123
	v_mfma_f32_32x32x16_bf16 v[16:31], v[238:241], v[92:95], v[16:31]
	v_fma_f32 v124, v124, s2, v14
	v_fma_f32 v125, v125, s2, v14
	v_exp_f32_e32 v124, v124
	v_exp_f32_e32 v125, v125
	v_fma_f32 v126, v126, s2, v14
	v_fma_f32 v127, v127, s2, v14
	v_exp_f32_e32 v126, v126
	v_exp_f32_e32 v127, v127
	s_branch .Ldq_smdone_9

.Ldq_noapply_12:
	s_waitcnt lgkmcnt(0)
	s_barrier
	s_add_i32 s14, s25, 1
	s_cmp_lg_u32 s25, 2
	s_cselect_b32 s25, s14, 0
	s_add_u32 s4, s4, 0x180000
	s_addc_u32 s5, s5, 0
	s_add_i32 s26, s26, 64
	s_add_i32 s27, s27, 1
	s_cmp_lt_u32 s27, 30
	s_cbranch_scc1 .Ldq_top_6
	v_lshl_add_u32 v1, s25, 13, v204
	v_add_u32_e32 v14, v1, v197
	v_add_u32_e32 v15, v1, v198
	ds_read_b128 v[2:5], v14
	ds_read_b128 v[6:9], v14 offset:4096
	ds_read_b128 v[10:13], v209
	ds_read_b128 v[242:245], v15
	ds_read_b128 v[246:249], v15 offset:4096
	ds_read_b128 v[210:213], v209 offset:1024
	s_bitcmp1_b32 s27, 0
	s_cselect_b32 s14, 0x5000, 0
	v_add_u32_e32 v250, s14, v201
	ds_read_b64_tr_b16 v[96:97], v250 offset:24576
	ds_read_b64_tr_b16 v[100:101], v250 offset:24640
	ds_read_b64_tr_b16 v[104:105], v250 offset:24704
	ds_read_b64_tr_b16 v[108:109], v250 offset:24768
	ds_read_b64_tr_b16 v[98:99], v250 offset:27136
	ds_read_b64_tr_b16 v[102:103], v250 offset:27200
	ds_read_b64_tr_b16 v[106:107], v250 offset:27264
	ds_read_b64_tr_b16 v[110:111], v250 offset:27328
	s_waitcnt lgkmcnt(11)
	v_mfma_f32_32x32x16_bf16 v[128:143], v[2:5], v[10:13], 0
	v_mfma_f32_32x32x16_bf16 v[112:127], v[6:9], v[10:13], 0
	s_waitcnt lgkmcnt(8)
	v_mfma_f32_32x32x16_bf16 v[128:143], v[242:245], v[210:213], v[128:143]
	v_mfma_f32_32x32x16_bf16 v[112:127], v[246:249], v[210:213], v[112:127]
	v_add_u32_e32 v14, v1, v199
	v_add_u32_e32 v15, v1, v200
	ds_read_b128 v[2:5], v14
	ds_read_b128 v[6:9], v14 offset:4096
	ds_read_b128 v[10:13], v209 offset:2048
	ds_read_b128 v[242:245], v15
	ds_read_b128 v[246:249], v15 offset:4096
	ds_read_b128 v[210:213], v209 offset:3072
	s_add_i32 s14, s27, 1
	s_bitcmp1_b32 s14, 0
	s_cselect_b32 s15, 0x5000, 0
	v_add3_u32 v251, s15, v193, v194
	s_waitcnt vmcnt(1)
	ds_write_b128 v251, v[148:151] offset:24576
	v_add3_u32 v251, s15, v195, v196
	s_waitcnt vmcnt(0)
	ds_write_b128 v251, v[152:155] offset:24576
	s_waitcnt lgkmcnt(5)
	v_mfma_f32_32x32x16_bf16 v[128:143], v[2:5], v[10:13], v[128:143]
	v_mfma_f32_32x32x16_bf16 v[112:127], v[6:9], v[10:13], v[112:127]
	s_waitcnt lgkmcnt(2)
	v_mfma_f32_32x32x16_bf16 v[128:143], v[242:245], v[210:213], v[128:143]
	v_mfma_f32_32x32x16_bf16 v[112:127], v[246:249], v[210:213], v[112:127]
	s_add_i32 s14, s26, 0xffffff60
	s_cmp_gt_u32 s14, 0xfffffea0
	s_cbranch_scc1 .Ldq_near_13
	s_sub_i32 s14, s26, 31
	s_cmpk_gt_i32 s14, 0x80
	s_cselect_b32 s14, 0x408, 0
	s_add_i32 s14, s18, s14
	v_mov_b32_e32 v1, s14
	ds_read_b32 v14, v1 offset:29312
	ds_read_b64_tr_b16 v[226:227], v250 offset:29696
	ds_read_b64_tr_b16 v[230:231], v250 offset:29760
	ds_read_b64_tr_b16 v[234:235], v250 offset:29824
	ds_read_b64_tr_b16 v[238:239], v250 offset:29888
	ds_read_b64_tr_b16 v[228:229], v250 offset:32256
	ds_read_b64_tr_b16 v[232:233], v250 offset:32320
	ds_read_b64_tr_b16 v[236:237], v250 offset:32384
	ds_read_b64_tr_b16 v[240:241], v250 offset:32448
	s_waitcnt lgkmcnt(8)
	s_nop 3
	v_mfma_f32_32x32x16_bf16 v[64:79], v[96:99], v[80:83], v[64:79]
	v_max3_f32 v225, v128, v129, v130
	v_max3_f32 v225, v225, v131, v132
	v_max3_f32 v225, v225, v133, v134
	v_max3_f32 v225, v225, v135, v136
	v_mfma_f32_32x32x16_bf16 v[48:63], v[100:103], v[80:83], v[48:63]
	v_max3_f32 v225, v225, v137, v138
	v_max3_f32 v225, v225, v139, v140
	v_max3_f32 v225, v225, v141, v142
	v_max3_f32 v225, v225, v143, v112
	v_mfma_f32_32x32x16_bf16 v[32:47], v[104:107], v[80:83], v[32:47]
	v_max3_f32 v225, v225, v113, v114
	v_max3_f32 v225, v225, v115, v116
	v_max3_f32 v225, v225, v117, v118
	v_max3_f32 v225, v225, v119, v120
	v_mfma_f32_32x32x16_bf16 v[16:31], v[108:111], v[80:83], v[16:31]
	v_max3_f32 v225, v225, v121, v122
	v_max3_f32 v225, v225, v123, v124
	v_max3_f32 v225, v225, v125, v126
	v_max_f32_e32 v225, v225, v127
	ds_read_b64_tr_b16 v[96:97], v250 offset:34816
	ds_read_b64_tr_b16 v[100:101], v250 offset:34880
	ds_read_b64_tr_b16 v[104:105], v250 offset:34944
	ds_read_b64_tr_b16 v[108:109], v250 offset:35008
	ds_read_b64_tr_b16 v[98:99], v250 offset:37376
	ds_read_b64_tr_b16 v[102:103], v250 offset:37440
	ds_read_b64_tr_b16 v[106:107], v250 offset:37504
	ds_read_b64_tr_b16 v[110:111], v250 offset:37568
	v_fma_f32 v225, v225, s2, v14
	v_mov_b32_e32 v2, v225
	v_mov_b32_e32 v3, v225
	s_nop 1
	v_permlane32_swap_b32 v2, v3
	s_nop 1
	s_nop 0
	v_max3_f32 v225, v225, v2, v3
	v_add_f32_e32 v2, 0x41000000, v208
	v_cmp_gt_f32_e32 vcc, v225, v2
	s_cbranch_vccz .Ldq_norescale_15
	v_max_f32_e32 v2, v225, v225
	v_max_f32_e32 v3, v208, v208
	v_max_f32_e32 v2, v3, v2
	v_sub_f32_e32 v3, v208, v2
	v_exp_f32_e32 v3, v3
	v_mov_b32_e32 v208, v2
	s_nop 0
	v_mul_f32_e32 v187, v187, v3
	v_mov_b32_e32 v214, v3
	s_mov_b32 s100, 1

.Ldq_noapply_17:
	s_waitcnt lgkmcnt(0)
	s_barrier
	s_add_i32 s27, s27, 1
	s_bitcmp1_b32 s27, 0
	s_cselect_b32 s14, 0x5000, 0
	v_add_u32_e32 v250, s14, v201
	ds_read_b64_tr_b16 v[96:97], v250 offset:24576
	ds_read_b64_tr_b16 v[100:101], v250 offset:24640
	ds_read_b64_tr_b16 v[104:105], v250 offset:24704
	ds_read_b64_tr_b16 v[108:109], v250 offset:24768
	ds_read_b64_tr_b16 v[98:99], v250 offset:27136
	ds_read_b64_tr_b16 v[102:103], v250 offset:27200
	ds_read_b64_tr_b16 v[106:107], v250 offset:27264
	ds_read_b64_tr_b16 v[110:111], v250 offset:27328
	ds_read_b64_tr_b16 v[226:227], v250 offset:29696
	ds_read_b64_tr_b16 v[230:231], v250 offset:29760
	ds_read_b64_tr_b16 v[234:235], v250 offset:29824
	ds_read_b64_tr_b16 v[238:239], v250 offset:29888
	ds_read_b64_tr_b16 v[228:229], v250 offset:32256
	ds_read_b64_tr_b16 v[232:233], v250 offset:32320
	ds_read_b64_tr_b16 v[236:237], v250 offset:32384
	ds_read_b64_tr_b16 v[240:241], v250 offset:32448
	s_waitcnt lgkmcnt(8)
	v_mfma_f32_32x32x16_bf16 v[64:79], v[96:99], v[80:83], v[64:79]
	v_mfma_f32_32x32x16_bf16 v[48:63], v[100:103], v[80:83], v[48:63]
	v_mfma_f32_32x32x16_bf16 v[32:47], v[104:107], v[80:83], v[32:47]
	v_mfma_f32_32x32x16_bf16 v[16:31], v[108:111], v[80:83], v[16:31]
	ds_read_b64_tr_b16 v[96:97], v250 offset:34816
	ds_read_b64_tr_b16 v[100:101], v250 offset:34880
	ds_read_b64_tr_b16 v[104:105], v250 offset:34944
	ds_read_b64_tr_b16 v[108:109], v250 offset:35008
	ds_read_b64_tr_b16 v[98:99], v250 offset:37376
	ds_read_b64_tr_b16 v[102:103], v250 offset:37440
	ds_read_b64_tr_b16 v[106:107], v250 offset:37504
	ds_read_b64_tr_b16 v[110:111], v250 offset:37568
	s_waitcnt lgkmcnt(8)
	v_mfma_f32_32x32x16_bf16 v[64:79], v[226:229], v[84:87], v[64:79]
	v_mfma_f32_32x32x16_bf16 v[48:63], v[230:233], v[84:87], v[48:63]
	v_mfma_f32_32x32x16_bf16 v[32:47], v[234:237], v[84:87], v[32:47]
	v_mfma_f32_32x32x16_bf16 v[16:31], v[238:241], v[84:87], v[16:31]
	ds_read_b64_tr_b16 v[226:227], v250 offset:39936
	ds_read_b64_tr_b16 v[230:231], v250 offset:40000
	ds_read_b64_tr_b16 v[234:235], v250 offset:40064
	ds_read_b64_tr_b16 v[238:239], v250 offset:40128
	ds_read_b64_tr_b16 v[228:229], v250 offset:42496
	ds_read_b64_tr_b16 v[232:233], v250 offset:42560
	ds_read_b64_tr_b16 v[236:237], v250 offset:42624
	ds_read_b64_tr_b16 v[240:241], v250 offset:42688
	s_waitcnt lgkmcnt(8)
	v_mfma_f32_32x32x16_bf16 v[64:79], v[96:99], v[88:91], v[64:79]
	v_mfma_f32_32x32x16_bf16 v[48:63], v[100:103], v[88:91], v[48:63]
	v_mfma_f32_32x32x16_bf16 v[32:47], v[104:107], v[88:91], v[32:47]
	v_mfma_f32_32x32x16_bf16 v[16:31], v[108:111], v[88:91], v[16:31]
	s_waitcnt lgkmcnt(0)
	v_mfma_f32_32x32x16_bf16 v[64:79], v[226:229], v[92:95], v[64:79]
	v_mfma_f32_32x32x16_bf16 v[48:63], v[230:233], v[92:95], v[48:63]
	v_mfma_f32_32x32x16_bf16 v[32:47], v[234:237], v[92:95], v[32:47]
	v_mfma_f32_32x32x16_bf16 v[16:31], v[238:241], v[92:95], v[16:31]
	s_waitcnt lgkmcnt(0)
	s_barrier
	s_setprio 0
	s_nop 7
	s_nop 7
	v_mov_b32_e32 v1, v187
	v_mov_b32_e32 v2, v0
	s_nop 0
	v_mbcnt_lo_u32_b32 v2, -1, v2
	v_mbcnt_hi_u32_b32 v2, -1, v2
	v_lshlrev_b32_e32 v2, 2, v2
	v_xor_b32_e32 v2, 0x80, v2
	ds_bpermute_b32 v2, v2, v1
	s_waitcnt lgkmcnt(0)
	v_add_f32_e32 v1, v1, v2
	v_div_scale_f32 v2, s[4:5], v1, v1, 1.0
	v_rcp_f32_e32 v3, v2
	s_nop 0
	v_fma_f32 v4, -v2, v3, 1.0
	v_fmac_f32_e32 v3, v4, v3
	v_div_scale_f32 v4, vcc, 1.0, v1, 1.0
	v_mul_f32_e32 v5, v4, v3
	v_fma_f32 v6, -v2, v5, v4
	v_fmac_f32_e32 v5, v6, v3
	v_fma_f32 v2, -v2, v5, v4
	v_div_fmas_f32 v2, v2, v3, v5
	v_div_fixup_f32 v6, v2, v1, 1.0
	v_cndmask_b32_e64 v1, 0, 1, s[0:1]
	v_cmp_ne_u32_e64 s[4:5], 1, v1
	s_andn2_b64 vcc, exec, s[0:1]
	s_mov_b64 s[0:1], -1
	s_cbranch_vccnz .LBB0_784
	s_load_dwordx2 s[100:101], s[56:57], 0x88
	global_load_dwordx4 v[228:231], v[164:165], off
	global_load_dwordx4 v[8:11], v[164:165], off offset:32
	global_load_dwordx4 v[140:143], v[164:165], off offset:64
	global_load_dwordx4 v[232:235], v[164:165], off offset:96
	global_load_dwordx4 v[148:151], v[164:165], off offset:128
	global_load_dwordx4 v[152:155], v[164:165], off offset:160
	global_load_dwordx4 v[156:159], v[164:165], off offset:192
	global_load_dwordx4 v[210:213], v[164:165], off offset:224
	v_mul_f32_e32 v1, v64, v6
	s_mov_b32 s0, 0x800000
	s_lshl_b64 s[14:15], s[8:9], 2
	v_lshlrev_b32_e32 v139, 2, v162
	s_waitcnt vmcnt(7)
	v_fma_f32 v1, -v160, v1, v228
	v_mul_f32_e32 v2, v65, v6
	v_fma_f32 v7, -v160, v2, v229
	v_mul_f32_e32 v3, v66, v6
	v_fma_f32 v86, -v160, v3, v230
	v_mul_f32_e32 v3, v67, v6
	v_fma_f32 v87, -v160, v3, v231
	v_mul_f32_e32 v3, v68, v6
	s_waitcnt vmcnt(6)
	v_fma_f32 v88, -v160, v3, v8
	v_mul_f32_e32 v3, v69, v6
	v_fma_f32 v89, -v160, v3, v9
	v_mul_f32_e32 v3, v70, v6
	v_fma_f32 v90, -v160, v3, v10
	v_mul_f32_e32 v3, v71, v6
	v_fma_f32 v91, -v160, v3, v11
	global_load_dwordx4 v[228:231], v[164:165], off offset:256
	v_mul_f32_e32 v3, v72, v6
	v_mul_f32_e32 v2, v7, v7
	v_fmac_f32_e32 v2, v1, v1
	v_fmac_f32_e32 v2, v86, v86
	v_fmac_f32_e32 v2, v87, v87
	v_fmac_f32_e32 v2, v88, v88
	v_fmac_f32_e32 v2, v89, v89
	v_fmac_f32_e32 v2, v90, v90
	v_fmac_f32_e32 v2, v91, v91
	v_pk_mul_f32 v[4:5], v[22:23], v[6:7] op_sel_hi:[1,0]
	s_waitcnt vmcnt(6)
	v_fma_f32 v95, -v160, v3, v140
	v_mul_f32_e32 v3, v73, v6
	v_fma_f32 v94, -v160, v3, v141
	v_mul_f32_e32 v3, v74, v6
	v_fma_f32 v93, -v160, v3, v142
	v_mul_f32_e32 v3, v75, v6
	v_fma_f32 v92, -v160, v3, v143
	global_load_dwordx4 v[8:11], v[164:165], off offset:288
	v_mul_f32_e32 v3, v76, v6
	v_fmac_f32_e32 v2, v95, v95
	v_fmac_f32_e32 v2, v94, v94
	v_fmac_f32_e32 v2, v93, v93
	v_fmac_f32_e32 v2, v92, v92
	s_waitcnt vmcnt(6)
	v_fma_f32 v99, -v160, v3, v232
	v_mul_f32_e32 v3, v77, v6
	v_fma_f32 v98, -v160, v3, v233
	v_mul_f32_e32 v3, v78, v6
	v_fma_f32 v97, -v160, v3, v234
	v_mul_f32_e32 v3, v79, v6
	v_fma_f32 v96, -v160, v3, v235
	global_load_dwordx4 v[140:143], v[164:165], off offset:320
	v_mul_f32_e32 v3, v48, v6
	v_fmac_f32_e32 v2, v99, v99
	v_fmac_f32_e32 v2, v98, v98
	v_fmac_f32_e32 v2, v97, v97
	v_fmac_f32_e32 v2, v96, v96
	s_waitcnt vmcnt(6)
	v_fma_f32 v103, -v160, v3, v148
	v_mul_f32_e32 v3, v49, v6
	v_fma_f32 v102, -v160, v3, v149
	v_mul_f32_e32 v3, v50, v6
	v_fma_f32 v101, -v160, v3, v150
	v_mul_f32_e32 v3, v51, v6
	v_fma_f32 v100, -v160, v3, v151
	global_load_dwordx4 v[232:235], v[164:165], off offset:352
	v_mul_f32_e32 v3, v52, v6
	v_fmac_f32_e32 v2, v103, v103
	v_fmac_f32_e32 v2, v102, v102
	v_fmac_f32_e32 v2, v101, v101
	v_fmac_f32_e32 v2, v100, v100
	s_waitcnt vmcnt(6)
	v_fma_f32 v107, -v160, v3, v152
	v_mul_f32_e32 v3, v53, v6
	v_fma_f32 v106, -v160, v3, v153
	v_mul_f32_e32 v3, v54, v6
	v_fma_f32 v105, -v160, v3, v154
	v_mul_f32_e32 v3, v55, v6
	v_fma_f32 v104, -v160, v3, v155
	global_load_dwordx4 v[148:151], v[164:165], off offset:384
	v_mul_f32_e32 v3, v56, v6
	v_fmac_f32_e32 v2, v107, v107
	v_fmac_f32_e32 v2, v106, v106
	v_fmac_f32_e32 v2, v105, v105
	v_fmac_f32_e32 v2, v104, v104
	s_waitcnt vmcnt(6)
	v_fma_f32 v111, -v160, v3, v156
	v_mul_f32_e32 v3, v57, v6
	v_fma_f32 v110, -v160, v3, v157
	v_mul_f32_e32 v3, v58, v6
	v_fma_f32 v109, -v160, v3, v158
	v_mul_f32_e32 v3, v59, v6
	v_fma_f32 v108, -v160, v3, v159
	global_load_dwordx4 v[152:155], v[164:165], off offset:416
	v_mul_f32_e32 v3, v60, v6
	v_fmac_f32_e32 v2, v111, v111
	v_fmac_f32_e32 v2, v110, v110
	v_fmac_f32_e32 v2, v109, v109
	v_fmac_f32_e32 v2, v108, v108
	s_waitcnt vmcnt(6)
	v_fma_f32 v115, -v160, v3, v210
	v_mul_f32_e32 v3, v61, v6
	v_fma_f32 v114, -v160, v3, v211
	v_mul_f32_e32 v3, v62, v6
	v_fma_f32 v113, -v160, v3, v212
	v_mul_f32_e32 v3, v63, v6
	v_fma_f32 v112, -v160, v3, v213
	global_load_dwordx4 v[156:159], v[164:165], off offset:448
	v_mul_f32_e32 v3, v32, v6
	v_fmac_f32_e32 v2, v115, v115
	v_fmac_f32_e32 v2, v114, v114
	v_fmac_f32_e32 v2, v113, v113
	v_fmac_f32_e32 v2, v112, v112
	s_waitcnt vmcnt(6)
	v_fma_f32 v119, -v160, v3, v228
	v_mul_f32_e32 v3, v33, v6
	v_fma_f32 v121, -v160, v3, v229
	v_mul_f32_e32 v3, v34, v6
	v_fma_f32 v118, -v160, v3, v230
	v_mul_f32_e32 v3, v35, v6
	v_fma_f32 v116, -v160, v3, v231
	global_load_dwordx4 v[210:213], v[164:165], off offset:480
	v_mul_f32_e32 v3, v36, v6
	v_fmac_f32_e32 v2, v119, v119
	v_fmac_f32_e32 v2, v121, v121
	v_fmac_f32_e32 v2, v118, v118
	v_fmac_f32_e32 v2, v116, v116
	s_waitcnt vmcnt(6)
	v_fma_f32 v123, -v160, v3, v8
	v_mul_f32_e32 v3, v37, v6
	v_fma_f32 v122, -v160, v3, v9
	v_mul_f32_e32 v3, v38, v6
	v_fma_f32 v120, -v160, v3, v10
	v_mul_f32_e32 v3, v39, v6
	v_fma_f32 v117, -v160, v3, v11
	v_mul_f32_e32 v3, v40, v6
	v_fmac_f32_e32 v2, v123, v123
	v_fmac_f32_e32 v2, v122, v122
	v_fmac_f32_e32 v2, v120, v120
	v_fmac_f32_e32 v2, v117, v117
	s_waitcnt vmcnt(5)
	v_fma_f32 v127, -v160, v3, v140
	v_mul_f32_e32 v3, v41, v6
	v_fma_f32 v126, -v160, v3, v141
	v_mul_f32_e32 v3, v42, v6
	v_fma_f32 v125, -v160, v3, v142
	v_mul_f32_e32 v3, v43, v6
	v_fma_f32 v124, -v160, v3, v143
	v_mul_f32_e32 v3, v44, v6
	v_fmac_f32_e32 v2, v127, v127
	v_fmac_f32_e32 v2, v126, v126
	v_fmac_f32_e32 v2, v125, v125
	v_fmac_f32_e32 v2, v124, v124
	s_waitcnt vmcnt(4)
	v_fma_f32 v131, -v160, v3, v232
	v_mul_f32_e32 v3, v45, v6
	v_fma_f32 v130, -v160, v3, v233
	v_mul_f32_e32 v3, v46, v6
	v_fma_f32 v129, -v160, v3, v234
	v_mul_f32_e32 v3, v47, v6
	v_fma_f32 v128, -v160, v3, v235
	v_mul_f32_e32 v3, v16, v6
	v_fmac_f32_e32 v2, v131, v131
	v_fmac_f32_e32 v2, v130, v130
	v_fmac_f32_e32 v2, v129, v129
	v_fmac_f32_e32 v2, v128, v128
	s_waitcnt vmcnt(3)
	v_fma_f32 v135, -v160, v3, v148
	v_mul_f32_e32 v3, v17, v6
	v_fma_f32 v134, -v160, v3, v149
	v_mul_f32_e32 v3, v18, v6
	v_fma_f32 v133, -v160, v3, v150
	v_mul_f32_e32 v3, v19, v6
	v_fma_f32 v132, -v160, v3, v151
	v_fmac_f32_e32 v2, v135, v135
	v_fmac_f32_e32 v2, v134, v134
	v_fmac_f32_e32 v2, v133, v133
	v_mul_f32_e32 v3, v20, v6
	v_fmac_f32_e32 v2, v132, v132
	s_waitcnt vmcnt(2)
	v_fma_f32 v137, -v160, v3, v152
	v_mul_f32_e32 v3, v21, v6
	v_fmac_f32_e32 v2, v137, v137
	v_fma_f32 v136, -v160, v3, v153
	v_pk_fma_f32 v[8:9], v[160:161], v[4:5], v[154:155] neg_lo:[1,0,0] neg_hi:[1,0,0]
	v_fmac_f32_e32 v2, v136, v136
	v_pk_mul_f32 v[4:5], v[8:9], v[8:9]
	v_pk_mul_f32 v[10:11], v[24:25], v[6:7] op_sel_hi:[1,0]
	v_add_f32_e32 v2, v4, v2
	v_add_f32_e32 v14, v5, v2
	s_waitcnt vmcnt(1)
	v_pk_fma_f32 v[12:13], v[160:161], v[10:11], v[156:157] neg_lo:[1,0,0] neg_hi:[1,0,0]
	s_nop 0
	v_pk_mul_f32 v[2:3], v[12:13], v[12:13]
	s_nop 0
	v_add_f32_e32 v2, v2, v14
	v_add_f32_e32 v14, v3, v2
	v_pk_mul_f32 v[2:3], v[26:27], v[6:7] op_sel_hi:[1,0]
	s_nop 0
	v_pk_fma_f32 v[10:11], v[160:161], v[2:3], v[158:159] neg_lo:[1,0,0] neg_hi:[1,0,0]
	s_nop 0
	v_pk_mul_f32 v[2:3], v[10:11], v[10:11]
	s_nop 0
	v_add_f32_e32 v2, v2, v14
	v_add_f32_e32 v82, v3, v2
	v_pk_mul_f32 v[14:15], v[28:29], v[6:7] op_sel_hi:[1,0]
	s_waitcnt vmcnt(0)
	v_pk_fma_f32 v[80:81], v[160:161], v[14:15], v[210:211] neg_lo:[1,0,0] neg_hi:[1,0,0]
	s_nop 0
	v_pk_mul_f32 v[2:3], v[80:81], v[80:81]
	s_nop 0
	v_add_f32_e32 v2, v2, v82
	v_add_f32_e32 v82, v3, v2
	v_pk_mul_f32 v[2:3], v[30:31], v[6:7] op_sel_hi:[1,0]
	s_waitcnt lgkmcnt(0)
	s_add_u32 s100, s100, s14
	s_addc_u32 s101, s101, s15
	global_load_dwordx4 v[16:19], v139, s[100:101]
	global_load_dwordx4 v[20:23], v139, s[100:101] offset:32
	global_load_dwordx4 v[24:27], v139, s[100:101] offset:64
	global_load_dwordx4 v[28:31], v139, s[100:101] offset:96
	global_load_dwordx4 v[32:35], v139, s[100:101] offset:128
	global_load_dwordx4 v[36:39], v139, s[100:101] offset:160
	global_load_dwordx4 v[40:43], v139, s[100:101] offset:192
	global_load_dwordx4 v[44:47], v139, s[100:101] offset:224
	global_load_dwordx4 v[48:51], v139, s[100:101] offset:256
	global_load_dwordx4 v[52:55], v139, s[100:101] offset:288
	global_load_dwordx4 v[56:59], v139, s[100:101] offset:320
	global_load_dwordx4 v[60:63], v139, s[100:101] offset:352
	global_load_dwordx4 v[64:67], v139, s[100:101] offset:384
	global_load_dwordx4 v[68:71], v139, s[100:101] offset:416
	global_load_dwordx4 v[72:75], v139, s[100:101] offset:448
	global_load_dwordx4 v[76:79], v139, s[100:101] offset:480
	s_nop 0
	v_pk_fma_f32 v[14:15], v[160:161], v[2:3], v[212:213] neg_lo:[1,0,0] neg_hi:[1,0,0]
	v_lshlrev_b32_e32 v4, 1, v162
	v_pk_mul_f32 v[2:3], v[14:15], v[14:15]
	v_mov_b32_e32 v5, v0
	v_add_f32_e32 v2, v2, v82
	v_add_f32_e32 v2, v3, v2
	v_mov_b32_e32 v3, v0
	s_nop 0
	v_mbcnt_lo_u32_b32 v3, -1, v3
	v_mbcnt_hi_u32_b32 v3, -1, v3
	v_lshlrev_b32_e32 v3, 2, v3
	v_xor_b32_e32 v3, 0x80, v3
	ds_bpermute_b32 v3, v3, v2
	s_waitcnt lgkmcnt(0)
	v_add_f32_e32 v2, v2, v3
	v_fmamk_f32 v2, v2, 0x3c000000, v217
	v_cmp_gt_f32_e32 vcc, s0, v2
	v_mul_f32_e32 v3, 0x4b800000, v2
	s_mov_b64 s[0:1], s[56:57]
	v_cndmask_b32_e32 v2, v2, v3, vcc
	v_rsq_f32_e32 v2, v2
	s_load_dwordx2 s[0:1], s[0:1], 0xf0
	v_mul_f32_e32 v3, 0x45800000, v2
	v_cndmask_b32_e32 v2, v2, v3, vcc
	v_mul_f32_e32 v138, v163, v2
	s_waitcnt lgkmcnt(0)
	v_lshl_add_u64 v[2:3], s[0:1], 0, v[178:179]
	v_lshl_add_u64 v[2:3], v[2:3], 0, s[36:37]
	v_lshl_add_u64 v[84:85], v[2:3], 0, v[4:5]
	s_mov_b64 s[0:1], 0x6a701000
	v_lshl_add_u64 v[82:83], v[84:85], 0, s[0:1]
	s_mov_b64 s[0:1], s[56:57]
	s_load_dwordx2 s[0:1], s[0:1], 0x88
	v_mul_f32_e32 v1, v1, v138
	s_waitcnt lgkmcnt(0)
	s_add_u32 s0, s0, s14
	s_addc_u32 s1, s1, s15
	s_waitcnt vmcnt(0)
	v_mul_f32_e32 v1, v16, v1
	v_mul_f32_e32 v2, v7, v138
	v_mul_f32_e32 v2, v17, v2
	v_cvt_pk_bf16_f32 v2, v1, v2
	v_mul_f32_e32 v1, v86, v138
	v_mul_f32_e32 v1, v18, v1
	v_mul_f32_e32 v3, v87, v138
	v_add_co_u32_e32 v4, vcc, s42, v84
	v_mul_f32_e32 v3, v19, v3
	s_nop 0
	v_addc_co_u32_e32 v5, vcc, 0, v85, vcc
	v_cvt_pk_bf16_f32 v3, v1, v3
	global_store_dwordx2 v[4:5], v[2:3], off
	v_mul_f32_e32 v1, v88, v138
	v_mul_f32_e32 v1, v20, v1
	v_mul_f32_e32 v2, v89, v138
	v_mul_f32_e32 v2, v21, v2
	v_mul_f32_e32 v3, v91, v138
	v_cvt_pk_bf16_f32 v2, v1, v2
	v_mul_f32_e32 v1, v90, v138
	v_mul_f32_e32 v3, v23, v3
	v_mul_f32_e32 v1, v22, v1
	v_cvt_pk_bf16_f32 v3, v1, v3
	global_store_dwordx2 v[82:83], v[2:3], off offset:16
	v_mul_f32_e32 v1, v95, v138
	v_mul_f32_e32 v1, v24, v1
	v_mul_f32_e32 v2, v94, v138
	v_mul_f32_e32 v2, v25, v2
	v_mul_f32_e32 v3, v92, v138
	v_cvt_pk_bf16_f32 v2, v1, v2
	v_mul_f32_e32 v1, v93, v138
	v_mul_f32_e32 v3, v27, v3
	v_mul_f32_e32 v1, v26, v1
	v_cvt_pk_bf16_f32 v3, v1, v3
	global_store_dwordx2 v[82:83], v[2:3], off offset:32
	v_mul_f32_e32 v1, v99, v138
	v_mul_f32_e32 v1, v28, v1
	v_mul_f32_e32 v2, v98, v138
	v_mul_f32_e32 v2, v29, v2
	v_mul_f32_e32 v3, v96, v138
	v_cvt_pk_bf16_f32 v2, v1, v2
	v_mul_f32_e32 v1, v97, v138
	v_mul_f32_e32 v3, v31, v3
	v_mul_f32_e32 v1, v30, v1
	v_cvt_pk_bf16_f32 v3, v1, v3
	global_store_dwordx2 v[82:83], v[2:3], off offset:48
	v_mul_f32_e32 v1, v103, v138
	v_mul_f32_e32 v1, v32, v1
	v_mul_f32_e32 v2, v102, v138
	v_mul_f32_e32 v2, v33, v2
	v_mul_f32_e32 v3, v100, v138
	v_cvt_pk_bf16_f32 v2, v1, v2
	v_mul_f32_e32 v1, v101, v138
	v_mul_f32_e32 v3, v35, v3
	v_mul_f32_e32 v1, v34, v1
	v_cvt_pk_bf16_f32 v3, v1, v3
	global_store_dwordx2 v[82:83], v[2:3], off offset:64
	v_mul_f32_e32 v1, v107, v138
	v_mul_f32_e32 v1, v36, v1
	v_mul_f32_e32 v2, v106, v138
	v_mul_f32_e32 v2, v37, v2
	v_mul_f32_e32 v3, v104, v138
	v_cvt_pk_bf16_f32 v2, v1, v2
	v_mul_f32_e32 v1, v105, v138
	v_mul_f32_e32 v3, v39, v3
	v_mul_f32_e32 v1, v38, v1
	v_cvt_pk_bf16_f32 v3, v1, v3
	global_store_dwordx2 v[82:83], v[2:3], off offset:80
	v_mul_f32_e32 v1, v111, v138
	v_mul_f32_e32 v1, v40, v1
	v_mul_f32_e32 v2, v110, v138
	v_mul_f32_e32 v2, v41, v2
	v_mul_f32_e32 v3, v108, v138
	v_cvt_pk_bf16_f32 v2, v1, v2
	v_mul_f32_e32 v1, v109, v138
	v_mul_f32_e32 v3, v43, v3
	v_mul_f32_e32 v1, v42, v1
	v_cvt_pk_bf16_f32 v3, v1, v3
	global_store_dwordx2 v[82:83], v[2:3], off offset:96
	v_mul_f32_e32 v1, v115, v138
	v_mul_f32_e32 v1, v44, v1
	v_mul_f32_e32 v2, v114, v138
	v_mul_f32_e32 v2, v45, v2
	v_mul_f32_e32 v3, v112, v138
	v_cvt_pk_bf16_f32 v2, v1, v2
	v_mul_f32_e32 v1, v113, v138
	v_mul_f32_e32 v3, v47, v3
	v_mul_f32_e32 v1, v46, v1
	v_cvt_pk_bf16_f32 v3, v1, v3
	global_store_dwordx2 v[82:83], v[2:3], off offset:112
	v_mul_f32_e32 v1, v119, v138
	v_mul_f32_e32 v1, v48, v1
	v_mul_f32_e32 v2, v121, v138
	v_mul_f32_e32 v2, v49, v2
	v_mul_f32_e32 v3, v116, v138
	v_cvt_pk_bf16_f32 v2, v1, v2
	v_mul_f32_e32 v1, v118, v138
	v_mul_f32_e32 v3, v51, v3
	v_mul_f32_e32 v1, v50, v1
	v_cvt_pk_bf16_f32 v3, v1, v3
	global_store_dwordx2 v[82:83], v[2:3], off offset:128
	v_mul_f32_e32 v1, v123, v138
	v_mul_f32_e32 v1, v52, v1
	v_mul_f32_e32 v2, v122, v138
	v_mul_f32_e32 v2, v53, v2
	v_mul_f32_e32 v3, v117, v138
	v_cvt_pk_bf16_f32 v2, v1, v2
	v_mul_f32_e32 v1, v120, v138
	v_mul_f32_e32 v3, v55, v3
	v_mul_f32_e32 v1, v54, v1
	v_cvt_pk_bf16_f32 v3, v1, v3
	global_store_dwordx2 v[82:83], v[2:3], off offset:144
	v_mul_f32_e32 v1, v127, v138
	v_mul_f32_e32 v1, v56, v1
	v_mul_f32_e32 v2, v126, v138
	v_mul_f32_e32 v2, v57, v2
	v_mul_f32_e32 v3, v124, v138
	v_cvt_pk_bf16_f32 v2, v1, v2
	v_mul_f32_e32 v1, v125, v138
	v_mul_f32_e32 v3, v59, v3
	v_mul_f32_e32 v1, v58, v1
	v_cvt_pk_bf16_f32 v3, v1, v3
	global_store_dwordx2 v[82:83], v[2:3], off offset:160
	v_mul_f32_e32 v1, v131, v138
	v_mul_f32_e32 v1, v60, v1
	v_mul_f32_e32 v2, v130, v138
	v_mul_f32_e32 v2, v61, v2
	v_mul_f32_e32 v3, v128, v138
	v_cvt_pk_bf16_f32 v2, v1, v2
	v_mul_f32_e32 v1, v129, v138
	v_mul_f32_e32 v3, v63, v3
	v_mul_f32_e32 v1, v62, v1
	v_cvt_pk_bf16_f32 v3, v1, v3
	global_store_dwordx2 v[82:83], v[2:3], off offset:176
	v_mul_f32_e32 v1, v135, v138
	v_mul_f32_e32 v1, v64, v1
	v_mul_f32_e32 v2, v134, v138
	v_mul_f32_e32 v2, v65, v2
	v_mul_f32_e32 v3, v132, v138
	v_cvt_pk_bf16_f32 v2, v1, v2
	v_mul_f32_e32 v1, v133, v138
	v_mul_f32_e32 v3, v67, v3
	v_mul_f32_e32 v1, v66, v1
	v_cvt_pk_bf16_f32 v3, v1, v3
	global_store_dwordx2 v[82:83], v[2:3], off offset:192
	v_mul_f32_e32 v1, v137, v138
	v_mul_f32_e32 v1, v1, v68
	v_mul_f32_e32 v2, v136, v138
	v_mul_f32_e32 v2, v2, v69
	v_mul_f32_e32 v3, v9, v138
	v_cvt_pk_bf16_f32 v2, v1, v2
	v_mul_f32_e32 v1, v8, v138
	v_mul_f32_e32 v3, v3, v71
	v_mul_f32_e32 v1, v1, v70
	v_cvt_pk_bf16_f32 v3, v1, v3
	global_store_dwordx2 v[82:83], v[2:3], off offset:208
	v_mul_f32_e32 v1, v12, v138
	v_mul_f32_e32 v1, v1, v72
	v_mul_f32_e32 v2, v13, v138
	v_mul_f32_e32 v2, v2, v73
	v_mul_f32_e32 v3, v11, v138
	v_cvt_pk_bf16_f32 v2, v1, v2
	v_mul_f32_e32 v1, v10, v138
	v_mul_f32_e32 v3, v3, v75
	v_mul_f32_e32 v1, v1, v74
	v_cvt_pk_bf16_f32 v3, v1, v3
	global_store_dwordx2 v[82:83], v[2:3], off offset:224
	v_mul_f32_e32 v1, v80, v138
	v_mul_f32_e32 v1, v1, v76
	v_mul_f32_e32 v2, v81, v138
	v_mul_f32_e32 v2, v2, v77
	v_mul_f32_e32 v3, v15, v138
	v_cvt_pk_bf16_f32 v2, v1, v2
	v_mul_f32_e32 v1, v14, v138
	v_mul_f32_e32 v3, v3, v79
	v_mul_f32_e32 v1, v1, v78
	v_cvt_pk_bf16_f32 v3, v1, v3
	global_store_dwordx2 v[82:83], v[2:3], off offset:240
	s_cbranch_execnz .LBB0_754
	s_branch .LBB0_785
